# v24 + GEMM K-loop head aligned to 64 bytes (placement check)
# speedup vs baseline: 1.0050x; 1.0049x over previous
.Lcw_skip:
	v_add_u32_e32 v128, 0x10000, v182
	ds_read_b128 v[0:3], v128
	ds_read_b128 v[4:7], v128 offset:1024
	ds_read_b128 v[8:11], v128 offset:2048
	ds_read_b128 v[12:15], v128 offset:3072
	s_mul_i32 s75, s71, s63
	s_and_b64 s[6:7], s[6:7], exec
	s_cselect_b32 s1, s75, s11
	s_add_i32 s6, s11, 0x100
	s_add_i32 s7, s10, 0x100
	s_add_i32 s3, s11, 0x180
	s_add_i32 s8, s11, s67
	s_mov_b32 m0, s39
	ds_read_b128 v[16:19], v183
	ds_read_b128 v[20:23], v183 offset:1024
	ds_read_b128 v[24:27], v183 offset:2048
	ds_read_b128 v[28:31], v183 offset:3072
	ds_read_b128 v[32:35], v183 offset:4096
	ds_read_b128 v[36:39], v183 offset:5120
	ds_read_b128 v[40:43], v183 offset:6144
	ds_read_b128 v[44:47], v183 offset:7168
	buffer_load_dwordx4 v178, s[16:19], s8 offen lds
	s_mov_b32 m0, s34
	s_nop 0
	buffer_load_dwordx4 v180, s[16:19], s8 offen lds
	s_waitcnt lgkmcnt(8)
	s_barrier
	s_waitcnt lgkmcnt(0)
	s_setprio 3
	s_waitcnt lgkmcnt(7)
	v_mfma_f32_16x16x32_bf16 v[48:51], v[0:3], v[16:19], 0
	v_mfma_f32_16x16x32_bf16 v[52:55], v[8:11], v[16:19], 0
	s_waitcnt lgkmcnt(5)
	v_mfma_f32_16x16x32_bf16 v[56:59], v[0:3], v[24:27], 0
	v_mfma_f32_16x16x32_bf16 v[60:63], v[8:11], v[24:27], 0
	s_waitcnt lgkmcnt(3)
	v_mfma_f32_16x16x32_bf16 v[64:67], v[0:3], v[32:35], 0
	v_mfma_f32_16x16x32_bf16 v[68:71], v[8:11], v[32:35], 0
	s_waitcnt lgkmcnt(1)
	v_mfma_f32_16x16x32_bf16 v[72:75], v[0:3], v[40:43], 0
	v_mfma_f32_16x16x32_bf16 v[76:79], v[8:11], v[40:43], 0
	v_mfma_f32_16x16x32_bf16 v[48:51], v[4:7], v[20:23], v[48:51]
	v_mfma_f32_16x16x32_bf16 v[52:55], v[12:15], v[20:23], v[52:55]
	v_mfma_f32_16x16x32_bf16 v[56:59], v[4:7], v[28:31], v[56:59]
	v_mfma_f32_16x16x32_bf16 v[60:63], v[12:15], v[28:31], v[60:63]
	v_mfma_f32_16x16x32_bf16 v[64:67], v[4:7], v[36:39], v[64:67]
	v_mfma_f32_16x16x32_bf16 v[68:71], v[12:15], v[36:39], v[68:71]
	s_waitcnt lgkmcnt(0)
	v_mfma_f32_16x16x32_bf16 v[72:75], v[4:7], v[44:47], v[72:75]
	v_mfma_f32_16x16x32_bf16 v[76:79], v[12:15], v[44:47], v[76:79]
	s_setprio 0
	s_barrier
	v_add_u32_e32 v129, 0x14000, v182
	s_mov_b32 s22, s18
	s_mov_b32 s23, s19
	s_mov_b32 m0, s98
	ds_read_b128 v[80:83], v129
	ds_read_b128 v[84:87], v129 offset:1024
	ds_read_b128 v[88:91], v129 offset:2048
	ds_read_b128 v[92:95], v129 offset:3072
	buffer_load_dwordx4 v179, s[20:23], s7 offen lds
	s_mov_b32 m0, s99
	s_nop 0
	buffer_load_dwordx4 v181, s[20:23], s7 offen lds
	s_barrier
	s_waitcnt lgkmcnt(0)
	s_setprio 3
	s_waitcnt lgkmcnt(3)
	v_mfma_f32_16x16x32_bf16 v[96:99], v[80:83], v[16:19], 0
	s_waitcnt lgkmcnt(1)
	v_mfma_f32_16x16x32_bf16 v[16:19], v[88:91], v[16:19], 0
	v_mfma_f32_16x16x32_bf16 v[104:107], v[84:87], v[20:23], v[96:99]
	s_waitcnt lgkmcnt(0)
	v_mfma_f32_16x16x32_bf16 v[16:19], v[92:95], v[20:23], v[16:19]
	v_mfma_f32_16x16x32_bf16 v[20:23], v[80:83], v[24:27], 0
	v_mfma_f32_16x16x32_bf16 v[24:27], v[88:91], v[24:27], 0
	v_mfma_f32_16x16x32_bf16 v[20:23], v[84:87], v[28:31], v[20:23]
	v_mfma_f32_16x16x32_bf16 v[24:27], v[92:95], v[28:31], v[24:27]
	v_mfma_f32_16x16x32_bf16 v[28:31], v[80:83], v[32:35], 0
	v_mfma_f32_16x16x32_bf16 v[32:35], v[88:91], v[32:35], 0
	v_mfma_f32_16x16x32_bf16 v[28:31], v[84:87], v[36:39], v[28:31]
	v_mfma_f32_16x16x32_bf16 v[32:35], v[92:95], v[36:39], v[32:35]
	v_mfma_f32_16x16x32_bf16 v[36:39], v[80:83], v[40:43], 0
	v_mfma_f32_16x16x32_bf16 v[40:43], v[88:91], v[40:43], 0
	v_mfma_f32_16x16x32_bf16 v[36:39], v[84:87], v[44:47], v[36:39]
	v_mfma_f32_16x16x32_bf16 v[40:43], v[92:95], v[44:47], v[40:43]
	s_setprio 0
	s_mov_b32 m0, s48
	s_barrier
	ds_read_b128 v[44:47], v183 offset:16384
	ds_read_b128 v[96:99], v183 offset:17408
	ds_read_b128 v[100:103], v183 offset:18432
	ds_read_b128 v[108:111], v183 offset:19456
	ds_read_b128 v[112:115], v183 offset:20480
	ds_read_b128 v[116:119], v183 offset:21504
	ds_read_b128 v[120:123], v183 offset:22528
	ds_read_b128 v[124:127], v183 offset:23552
	buffer_load_dwordx4 v178, s[16:19], s6 offen lds
	s_mov_b32 m0, s97
	s_nop 0
	buffer_load_dwordx4 v180, s[16:19], s6 offen lds
	s_barrier
	s_waitcnt lgkmcnt(0)
	s_setprio 3
	s_waitcnt lgkmcnt(7)
	v_mfma_f32_16x16x32_bf16 v[130:133], v[0:3], v[44:47], 0
	s_waitcnt lgkmcnt(5)
	v_mfma_f32_16x16x32_bf16 v[140:143], v[0:3], v[100:103], 0
	s_waitcnt lgkmcnt(3)
	v_mfma_f32_16x16x32_bf16 v[148:151], v[0:3], v[112:115], 0
	s_waitcnt lgkmcnt(1)
	v_mfma_f32_16x16x32_bf16 v[0:3], v[0:3], v[120:123], 0
	v_mfma_f32_16x16x32_bf16 v[132:135], v[4:7], v[96:99], v[130:133]
	v_mfma_f32_16x16x32_bf16 v[140:143], v[4:7], v[108:111], v[140:143]
	v_mfma_f32_16x16x32_bf16 v[148:151], v[4:7], v[116:119], v[148:151]
	s_waitcnt lgkmcnt(0)
	v_mfma_f32_16x16x32_bf16 v[0:3], v[4:7], v[124:127], v[0:3]
	v_mfma_f32_16x16x32_bf16 v[4:7], v[8:11], v[120:123], 0
	v_mfma_f32_16x16x32_bf16 v[136:139], v[8:11], v[44:47], 0
	v_mfma_f32_16x16x32_bf16 v[144:147], v[8:11], v[100:103], 0
	v_mfma_f32_16x16x32_bf16 v[152:155], v[8:11], v[112:115], 0
	v_mfma_f32_16x16x32_bf16 v[8:11], v[12:15], v[124:127], v[4:7]
	v_mfma_f32_16x16x32_bf16 v[136:139], v[12:15], v[96:99], v[136:139]
	v_mfma_f32_16x16x32_bf16 v[144:147], v[12:15], v[108:111], v[144:147]
	v_mfma_f32_16x16x32_bf16 v[152:155], v[12:15], v[116:119], v[152:155]
	s_setprio 0
	s_barrier
	s_add_i32 s7, s7, s62
	s_mov_b32 m0, s93
	s_nop 0
	buffer_load_dwordx4 v179, s[20:23], s7 offen lds
	s_mov_b32 m0, s94
	s_nop 0
	buffer_load_dwordx4 v181, s[20:23], s7 offen lds
	s_waitcnt vmcnt(6)
	s_barrier
	s_setprio 3
	v_mfma_f32_16x16x32_bf16 v[4:7], v[80:83], v[44:47], 0
	v_mfma_f32_16x16x32_bf16 v[12:15], v[84:87], v[96:99], v[4:7]
	v_mfma_f32_16x16x32_bf16 v[4:7], v[88:91], v[44:47], 0
	v_mfma_f32_16x16x32_bf16 v[44:47], v[92:95], v[96:99], v[4:7]
	v_mfma_f32_16x16x32_bf16 v[4:7], v[80:83], v[100:103], 0
	v_mfma_f32_16x16x32_bf16 v[156:159], v[84:87], v[108:111], v[4:7]
	v_mfma_f32_16x16x32_bf16 v[4:7], v[88:91], v[100:103], 0
	v_mfma_f32_16x16x32_bf16 v[168:171], v[92:95], v[108:111], v[4:7]
	v_mfma_f32_16x16x32_bf16 v[4:7], v[80:83], v[112:115], 0
	v_mfma_f32_16x16x32_bf16 v[172:175], v[84:87], v[116:119], v[4:7]
	v_mfma_f32_16x16x32_bf16 v[4:7], v[88:91], v[112:115], 0
	v_mfma_f32_16x16x32_bf16 v[184:187], v[92:95], v[116:119], v[4:7]
	v_mfma_f32_16x16x32_bf16 v[4:7], v[80:83], v[120:123], 0
	v_mfma_f32_16x16x32_bf16 v[202:205], v[84:87], v[124:127], v[4:7]
	v_mfma_f32_16x16x32_bf16 v[4:7], v[88:91], v[120:123], 0
	v_mfma_f32_16x16x32_bf16 v[206:209], v[92:95], v[124:127], v[4:7]
	s_setprio 0
	v_add_u32_e32 v130, 0x18000, v182
	s_barrier
	s_nop 3
	ds_read_b128 v[4:7], v130
	ds_read_b128 v[210:213], v130 offset:1024
	ds_read_b128 v[214:217], v130 offset:2048
	ds_read_b128 v[218:221], v130 offset:3072
	s_add_i32 s6, s6, s61
	s_mov_b32 m0, s95
	ds_read_b128 v[88:91], v183 offset:32768
	ds_read_b128 v[92:95], v183 offset:33792
	ds_read_b128 v[222:225], v183 offset:34816
	ds_read_b128 v[226:229], v183 offset:35840
	ds_read_b128 v[230:233], v183 offset:36864
	ds_read_b128 v[234:237], v183 offset:37888
	ds_read_b128 v[238:241], v183 offset:38912
	ds_read_b128 v[242:245], v183 offset:39936
	buffer_load_dwordx4 v178, s[16:19], s6 offen lds
	s_mov_b32 m0, s27
	s_nop 0
	buffer_load_dwordx4 v180, s[16:19], s6 offen lds
	s_waitcnt lgkmcnt(8)
	s_barrier
	s_waitcnt lgkmcnt(0)
	s_setprio 3
	s_waitcnt lgkmcnt(7)
	v_mfma_f32_16x16x32_bf16 v[48:51], v[4:7], v[88:91], v[48:51]
	s_waitcnt lgkmcnt(6)
	v_mfma_f32_16x16x32_bf16 v[116:119], v[210:213], v[92:95], v[48:51]
	v_mfma_f32_16x16x32_bf16 v[48:51], v[214:217], v[88:91], v[52:55]
	v_mfma_f32_16x16x32_bf16 v[112:115], v[218:221], v[92:95], v[48:51]
	s_waitcnt lgkmcnt(5)
	v_mfma_f32_16x16x32_bf16 v[48:51], v[4:7], v[222:225], v[56:59]
	s_waitcnt lgkmcnt(4)
	v_mfma_f32_16x16x32_bf16 v[100:103], v[210:213], v[226:229], v[48:51]
	v_mfma_f32_16x16x32_bf16 v[48:51], v[214:217], v[222:225], v[60:63]
	v_mfma_f32_16x16x32_bf16 v[96:99], v[218:221], v[226:229], v[48:51]
	s_waitcnt lgkmcnt(3)
	v_mfma_f32_16x16x32_bf16 v[48:51], v[4:7], v[230:233], v[64:67]
	s_waitcnt lgkmcnt(2)
	v_mfma_f32_16x16x32_bf16 v[84:87], v[210:213], v[234:237], v[48:51]
	v_mfma_f32_16x16x32_bf16 v[48:51], v[214:217], v[230:233], v[68:71]
	v_mfma_f32_16x16x32_bf16 v[80:83], v[218:221], v[234:237], v[48:51]
	s_waitcnt lgkmcnt(1)
	v_mfma_f32_16x16x32_bf16 v[48:51], v[4:7], v[238:241], v[72:75]
	s_waitcnt lgkmcnt(0)
	v_mfma_f32_16x16x32_bf16 v[52:55], v[210:213], v[242:245], v[48:51]
	v_mfma_f32_16x16x32_bf16 v[48:51], v[214:217], v[238:241], v[76:79]
	v_mfma_f32_16x16x32_bf16 v[48:51], v[218:221], v[242:245], v[48:51]
	s_setprio 0
	s_barrier
	v_add_u32_e32 v131, 0x1c000, v182
	s_add_i32 s6, s10, 0x180
	s_mov_b32 m0, s26
	ds_read_b128 v[246:249], v131
	ds_read_b128 v[250:253], v131 offset:1024
	ds_read_b128 v[192:195], v131 offset:2048
	ds_read_b128 v[188:191], v131 offset:3072
	buffer_load_dwordx4 v179, s[20:23], s6 offen lds
	s_mov_b32 m0, s29
	s_nop 0
	buffer_load_dwordx4 v181, s[20:23], s6 offen lds
	s_barrier
; #define PG8_MMA(ai, bj, At, Bt) do { __builtin_amdgcn_s_setprio(3); _Pragma("unroll") for (int m = 0; m < 4; ++m) _Pragma("unroll") for (int n = 0; n < 2; ++n) _Pragma("unroll") for (int k = 0; k < 2; ++k) \
;         acc[ai][bj][m][n] = __builtin_amdgcn_mfma_f32_16x16x32_bf16(Bt[n][k], At[m][k], acc[ai][bj][m][n], 0, 0, 0); __builtin_amdgcn_s_setprio(0); } while (0)
; __device__ __forceinline__ void gemm_phase(LAS unsigned char* lds, const GemmD& g, const EpiG& E) {
;     ...
;         { const int t = 0; PG8_KBODY(PG8_MMA0); }
;         for (int t = 2; t < nt; t += 2) { PG8_KBODY(PG8_MMA); }
	s_waitcnt lgkmcnt(0)
	s_setprio 3
	s_waitcnt lgkmcnt(1)
	v_mfma_f32_16x16x32_bf16 v[16:19], v[192:195], v[88:91], v[16:19]
	s_waitcnt lgkmcnt(0)
	v_mfma_f32_16x16x32_bf16 v[120:123], v[188:191], v[92:95], v[16:19]
	v_mfma_f32_16x16x32_bf16 v[16:19], v[246:249], v[222:225], v[20:23]
	v_mfma_f32_16x16x32_bf16 v[108:111], v[250:253], v[226:229], v[16:19]
	v_mfma_f32_16x16x32_bf16 v[16:19], v[192:195], v[222:225], v[24:27]
	v_mfma_f32_16x16x32_bf16 v[56:59], v[246:249], v[88:91], v[104:107]
	v_mfma_f32_16x16x32_bf16 v[104:107], v[188:191], v[226:229], v[16:19]
	v_mfma_f32_16x16x32_bf16 v[16:19], v[246:249], v[230:233], v[28:31]
	v_mfma_f32_16x16x32_bf16 v[124:127], v[250:253], v[92:95], v[56:59]
	v_mfma_f32_16x16x32_bf16 v[92:95], v[250:253], v[234:237], v[16:19]
	v_mfma_f32_16x16x32_bf16 v[16:19], v[192:195], v[230:233], v[32:35]
	v_mfma_f32_16x16x32_bf16 v[88:91], v[188:191], v[234:237], v[16:19]
	v_mfma_f32_16x16x32_bf16 v[16:19], v[246:249], v[238:241], v[36:39]
	v_mfma_f32_16x16x32_bf16 v[68:71], v[250:253], v[242:245], v[16:19]
	v_mfma_f32_16x16x32_bf16 v[16:19], v[192:195], v[238:241], v[40:43]
	v_mfma_f32_16x16x32_bf16 v[60:63], v[188:191], v[242:245], v[16:19]
	s_setprio 0
	s_mov_b32 m0, s28
	s_barrier
	ds_read_b128 v[24:27], v183 offset:49152
	ds_read_b128 v[28:31], v183 offset:50176
	ds_read_b128 v[40:43], v183 offset:51200
	ds_read_b128 v[222:225], v183 offset:52224
	ds_read_b128 v[226:229], v183 offset:53248
	ds_read_b128 v[230:233], v183 offset:54272
	ds_read_b128 v[234:237], v183 offset:55296
	ds_read_b128 v[238:241], v183 offset:56320
	buffer_load_dwordx4 v178, s[16:19], s3 offen lds
	s_mov_b32 m0, s92
	s_nop 0
	buffer_load_dwordx4 v180, s[16:19], s3 offen lds
	s_barrier
	s_waitcnt lgkmcnt(0)
	s_setprio 3
	s_waitcnt lgkmcnt(7)
	v_mfma_f32_16x16x32_bf16 v[16:19], v[4:7], v[24:27], v[132:135]
	s_waitcnt lgkmcnt(6)
	v_mfma_f32_16x16x32_bf16 v[64:67], v[210:213], v[28:31], v[16:19]
	v_mfma_f32_16x16x32_bf16 v[16:19], v[214:217], v[24:27], v[136:139]
	v_mfma_f32_16x16x32_bf16 v[56:59], v[218:221], v[28:31], v[16:19]
	s_waitcnt lgkmcnt(5)
	v_mfma_f32_16x16x32_bf16 v[16:19], v[4:7], v[40:43], v[140:143]
	s_waitcnt lgkmcnt(4)
	v_mfma_f32_16x16x32_bf16 v[36:39], v[210:213], v[222:225], v[16:19]
	v_mfma_f32_16x16x32_bf16 v[16:19], v[214:217], v[40:43], v[144:147]
	v_mfma_f32_16x16x32_bf16 v[32:35], v[218:221], v[222:225], v[16:19]
	s_waitcnt lgkmcnt(3)
	v_mfma_f32_16x16x32_bf16 v[16:19], v[4:7], v[226:229], v[148:151]
	s_waitcnt lgkmcnt(1)
	v_mfma_f32_16x16x32_bf16 v[0:3], v[4:7], v[234:237], v[0:3]
	v_mfma_f32_16x16x32_bf16 v[20:23], v[210:213], v[230:233], v[16:19]
	v_mfma_f32_16x16x32_bf16 v[16:19], v[214:217], v[226:229], v[152:155]
	s_waitcnt lgkmcnt(0)
	v_mfma_f32_16x16x32_bf16 v[4:7], v[210:213], v[238:241], v[0:3]
	v_mfma_f32_16x16x32_bf16 v[0:3], v[214:217], v[234:237], v[8:11]
	v_mfma_f32_16x16x32_bf16 v[16:19], v[218:221], v[230:233], v[16:19]
	v_mfma_f32_16x16x32_bf16 v[0:3], v[218:221], v[238:241], v[0:3]
	s_setprio 0
	s_barrier
	s_add_i32 s6, s6, s62
	s_mov_b32 m0, s96
	s_nop 0
	buffer_load_dwordx4 v179, s[20:23], s6 offen lds
	s_mov_b32 m0, s35
	s_nop 0
	buffer_load_dwordx4 v181, s[20:23], s6 offen lds
	s_waitcnt vmcnt(6)
	s_barrier
	s_setprio 3
	v_mfma_f32_16x16x32_bf16 v[8:11], v[246:249], v[24:27], v[12:15]
	v_mfma_f32_16x16x32_bf16 v[76:79], v[250:253], v[28:31], v[8:11]
	v_mfma_f32_16x16x32_bf16 v[8:11], v[192:195], v[24:27], v[44:47]
	v_mfma_f32_16x16x32_bf16 v[72:75], v[188:191], v[28:31], v[8:11]
	v_mfma_f32_16x16x32_bf16 v[8:11], v[246:249], v[40:43], v[156:159]
	v_mfma_f32_16x16x32_bf16 v[44:47], v[250:253], v[222:225], v[8:11]
	v_mfma_f32_16x16x32_bf16 v[8:11], v[192:195], v[40:43], v[168:171]
	v_mfma_f32_16x16x32_bf16 v[40:43], v[188:191], v[222:225], v[8:11]
	v_mfma_f32_16x16x32_bf16 v[8:11], v[246:249], v[226:229], v[172:175]
	v_mfma_f32_16x16x32_bf16 v[28:31], v[250:253], v[230:233], v[8:11]
	v_mfma_f32_16x16x32_bf16 v[8:11], v[192:195], v[226:229], v[184:187]
	v_mfma_f32_16x16x32_bf16 v[24:27], v[188:191], v[230:233], v[8:11]
	v_mfma_f32_16x16x32_bf16 v[8:11], v[246:249], v[234:237], v[202:205]
	v_mfma_f32_16x16x32_bf16 v[12:15], v[250:253], v[238:241], v[8:11]
	v_mfma_f32_16x16x32_bf16 v[8:11], v[192:195], v[234:237], v[206:209]
	v_mfma_f32_16x16x32_bf16 v[8:11], v[188:191], v[238:241], v[8:11]
	s_setprio 0
	s_add_i32 s6, s10, 0x200
	s_mov_b32 s7, 4
	s_barrier
	.p2align 6
